# out-proj epilogue: second 64-row half's 16 four-lane ss atomics also batched into one 256-byte atomic
# speedup vs baseline: 1.0380x; 1.0007x over previous
; DI float bflo(unsigned v) { return __uint_as_float(v << 16); }
; DI float bfhi(unsigned v) { return __uint_as_float(v & 0xffff0000u); }
; template <int EPI>
; DI void gemm_tile(const Params& p, int layer, int mt, int nt, u16* sm, int wv) {
;     ...
;       for (int t = 0; t < 16; ++t) {
;         const int row = (lane >> 4) + 4 * t;
;         const f32x4 a4 = *(const f32x4*)(stg + row * 68 + kc * 4);
;         const float v0 = bflo(xb[t][0]) + a4[0], v1 = bfhi(xb[t][0]) + a4[1], v2 = bflo(xb[t][1]) + a4[2], v3 = bfhi(xb[t][1]) + a4[3];
;         float sq = v0 * v0 + v1 * v1 + v2 * v2 + v3 * v3;
;         u32x2 pv = {pk2(v0, v1), pk2(v2, v3)};
;         if (has_next) *(u32x2*)(xrow + (size_t)row * DM) = pv;
;         else *(u32x2*)(x2row + (size_t)row * DM) = pv;
;         sq += shx(sq, lane, 1); sq += shx(sq, lane, 2); sq += shx(sq, lane, 4); sq += shx(sq, lane, 8);
;         if (kc == 0) atomicAdd(ssn + mrow0 + row, sq);
.LBB0_439:
	v_pk_mul_f32 v[36:37], v[40:41], v[40:41]
	v_pk_mul_f32 v[40:41], v[42:43], v[42:43]
	v_add_f32_e32 v0, v36, v37
	v_add_f32_e32 v0, v40, v0
	v_add_f32_e32 v0, v41, v0
	s_nop 1
	v_mov_b32_dpp v36, v0 quad_perm:[1,0,3,2] row_mask:0xf bank_mask:0xf
	s_waitcnt lgkmcnt(0)
	v_add_f32_e32 v0, v0, v36
	s_nop 1
	v_mov_b32_dpp v36, v0 quad_perm:[2,3,0,1] row_mask:0xf bank_mask:0xf
	s_waitcnt lgkmcnt(0)
	v_add_f32_e32 v0, v0, v36
	s_nop 1
	v_mov_b32_dpp v36, v0 row_half_mirror row_mask:0xf bank_mask:0xf
	s_waitcnt lgkmcnt(0)
	v_add_f32_e32 v0, v0, v36
	s_nop 1
	v_mov_b32_dpp v36, v0 row_mirror row_mask:0xf bank_mask:0xf
	v_add_f32_e32 v146, v0, v36
	v_cmp_eq_u32_e64 s[2:3], 0, v180
	s_nop 1
	v_cndmask_b32_e64 v147, v147, v146, s[2:3]
.LBB0_441:
	ds_read_b128 v[40:43], v69 offset:1088
	s_waitcnt lgkmcnt(1)
	v_lshlrev_b32_e32 v36, 16, v34
	v_and_b32_e32 v37, 0xffff0000, v34
	v_lshlrev_b32_e32 v34, 16, v35
	v_and_b32_e32 v35, 0xffff0000, v35
	s_waitcnt lgkmcnt(0)
	v_pk_add_f32 v[36:37], v[40:41], v[36:37]
	v_pk_add_f32 v[34:35], v[42:43], v[34:35]
	v_pk_mul_f32 v[40:41], v[36:37], v[36:37]
	v_pk_mul_f32 v[42:43], v[34:35], v[34:35]
	v_add_f32_e32 v40, v40, v41
	v_lshlrev_b32_e32 v0, 10, v132
	v_add_f32_e32 v40, v42, v40
	v_add_f32_e32 v40, v43, v40
	v_cndmask_b32_e64 v11, v39, v11, s[34:35]
	v_cndmask_b32_e64 v10, v38, v10, s[34:35]
	v_lshlrev_b32_e32 v0, 1, v0
	v_cvt_pk_bf16_f32 v36, v36, v37
	v_cvt_pk_bf16_f32 v37, v34, v35
	v_lshl_add_u64 v[34:35], v[10:11], 0, v[0:1]
	s_nop 1
	v_mov_b32_dpp v0, v40 quad_perm:[1,0,3,2] row_mask:0xf bank_mask:0xf
	global_store_dwordx2 v[34:35], v[36:37], off
	v_lshl_add_u64 v[4:5], v[4:5], 2, s[0:1]
	s_waitcnt lgkmcnt(0)
	v_add_f32_e32 v0, v40, v0
	s_nop 1
	v_mov_b32_dpp v34, v0 quad_perm:[2,3,0,1] row_mask:0xf bank_mask:0xf
	s_waitcnt lgkmcnt(0)
	v_add_f32_e32 v0, v0, v34
	s_nop 1
	v_mov_b32_dpp v34, v0 row_half_mirror row_mask:0xf bank_mask:0xf
	s_waitcnt lgkmcnt(0)
	v_add_f32_e32 v0, v0, v34
	s_nop 1
	v_mov_b32_dpp v34, v0 row_mirror row_mask:0xf bank_mask:0xf
	v_add_f32_e32 v146, v0, v34
	v_cmp_eq_u32_e64 s[2:3], 1, v180
	s_nop 1
	v_cndmask_b32_e64 v147, v147, v146, s[2:3]
.LBB0_443:
	s_waitcnt lgkmcnt(0)
	ds_read_b128 v[34:37], v69 offset:2176
	v_lshlrev_b32_e32 v38, 16, v32
	v_and_b32_e32 v39, 0xffff0000, v32
	v_lshlrev_b32_e32 v32, 16, v33
	v_and_b32_e32 v33, 0xffff0000, v33
	s_waitcnt lgkmcnt(0)
	v_pk_add_f32 v[34:35], v[34:35], v[38:39]
	v_pk_add_f32 v[32:33], v[36:37], v[32:33]
	v_pk_mul_f32 v[36:37], v[34:35], v[34:35]
	v_pk_mul_f32 v[38:39], v[32:33], v[32:33]
	v_add_f32_e32 v36, v36, v37
	v_lshlrev_b32_e32 v0, 10, v130
	v_add_f32_e32 v36, v38, v36
	v_add_f32_e32 v36, v39, v36
	v_lshlrev_b32_e32 v0, 1, v0
	v_cvt_pk_bf16_f32 v34, v34, v35
	v_cvt_pk_bf16_f32 v35, v32, v33
	v_lshl_add_u64 v[32:33], v[10:11], 0, v[0:1]
	s_nop 1
	v_mov_b32_dpp v0, v36 quad_perm:[1,0,3,2] row_mask:0xf bank_mask:0xf
	global_store_dwordx2 v[32:33], v[34:35], off
	s_waitcnt lgkmcnt(0)
	v_add_f32_e32 v0, v36, v0
	s_nop 1
	v_mov_b32_dpp v32, v0 quad_perm:[2,3,0,1] row_mask:0xf bank_mask:0xf
	s_waitcnt lgkmcnt(0)
	v_add_f32_e32 v0, v0, v32
	s_nop 1
	v_mov_b32_dpp v32, v0 row_half_mirror row_mask:0xf bank_mask:0xf
	s_waitcnt lgkmcnt(0)
	v_add_f32_e32 v0, v0, v32
	s_nop 1
	v_mov_b32_dpp v32, v0 row_mirror row_mask:0xf bank_mask:0xf
	v_add_f32_e32 v146, v0, v32
	v_cmp_eq_u32_e64 s[2:3], 2, v180
	s_nop 1
	v_cndmask_b32_e64 v147, v147, v146, s[2:3]
.LBB0_445:
	s_waitcnt lgkmcnt(0)
	ds_read_b128 v[32:35], v69 offset:3264
	v_lshlrev_b32_e32 v36, 16, v30
	v_and_b32_e32 v37, 0xffff0000, v30
	v_lshlrev_b32_e32 v30, 16, v31
	v_and_b32_e32 v31, 0xffff0000, v31
	s_waitcnt lgkmcnt(0)
	v_pk_add_f32 v[32:33], v[32:33], v[36:37]
	v_pk_add_f32 v[30:31], v[34:35], v[30:31]
	v_pk_mul_f32 v[34:35], v[32:33], v[32:33]
	v_pk_mul_f32 v[36:37], v[30:31], v[30:31]
	v_add_f32_e32 v34, v34, v35
	v_lshlrev_b32_e32 v0, 10, v128
	v_add_f32_e32 v34, v36, v34
	v_add_f32_e32 v34, v37, v34
	v_lshlrev_b32_e32 v0, 1, v0
	v_cvt_pk_bf16_f32 v32, v32, v33
	v_cvt_pk_bf16_f32 v33, v30, v31
	v_lshl_add_u64 v[30:31], v[10:11], 0, v[0:1]
	s_nop 1
	v_mov_b32_dpp v0, v34 quad_perm:[1,0,3,2] row_mask:0xf bank_mask:0xf
	global_store_dwordx2 v[30:31], v[32:33], off
	s_waitcnt lgkmcnt(0)
	v_add_f32_e32 v0, v34, v0
	s_nop 1
	v_mov_b32_dpp v30, v0 quad_perm:[2,3,0,1] row_mask:0xf bank_mask:0xf
	s_waitcnt lgkmcnt(0)
	v_add_f32_e32 v0, v0, v30
	s_nop 1
	v_mov_b32_dpp v30, v0 row_half_mirror row_mask:0xf bank_mask:0xf
	s_waitcnt lgkmcnt(0)
	v_add_f32_e32 v0, v0, v30
	s_nop 1
	v_mov_b32_dpp v30, v0 row_mirror row_mask:0xf bank_mask:0xf
	v_add_f32_e32 v146, v0, v30
	v_cmp_eq_u32_e64 s[2:3], 3, v180
	s_nop 1
	v_cndmask_b32_e64 v147, v147, v146, s[2:3]
.LBB0_447:
	s_waitcnt lgkmcnt(0)
	ds_read_b128 v[30:33], v69 offset:4352
	v_lshlrev_b32_e32 v34, 16, v28
	v_and_b32_e32 v35, 0xffff0000, v28
	v_lshlrev_b32_e32 v28, 16, v29
	v_and_b32_e32 v29, 0xffff0000, v29
	s_waitcnt lgkmcnt(0)
	v_pk_add_f32 v[30:31], v[30:31], v[34:35]
	v_pk_add_f32 v[28:29], v[32:33], v[28:29]
	v_pk_mul_f32 v[32:33], v[30:31], v[30:31]
	v_pk_mul_f32 v[34:35], v[28:29], v[28:29]
	v_add_f32_e32 v32, v32, v33
	v_lshlrev_b32_e32 v0, 10, v126
	v_add_f32_e32 v32, v34, v32
	v_add_f32_e32 v32, v35, v32
	v_lshlrev_b32_e32 v0, 1, v0
	v_cvt_pk_bf16_f32 v30, v30, v31
	v_cvt_pk_bf16_f32 v31, v28, v29
	v_lshl_add_u64 v[28:29], v[10:11], 0, v[0:1]
	s_nop 1
	v_mov_b32_dpp v0, v32 quad_perm:[1,0,3,2] row_mask:0xf bank_mask:0xf
	global_store_dwordx2 v[28:29], v[30:31], off
	s_waitcnt lgkmcnt(0)
	v_add_f32_e32 v0, v32, v0
	s_nop 1
	v_mov_b32_dpp v28, v0 quad_perm:[2,3,0,1] row_mask:0xf bank_mask:0xf
	s_waitcnt lgkmcnt(0)
	v_add_f32_e32 v0, v0, v28
	s_nop 1
	v_mov_b32_dpp v28, v0 row_half_mirror row_mask:0xf bank_mask:0xf
	s_waitcnt lgkmcnt(0)
	v_add_f32_e32 v0, v0, v28
	s_nop 1
	v_mov_b32_dpp v28, v0 row_mirror row_mask:0xf bank_mask:0xf
	v_add_f32_e32 v146, v0, v28
	v_cmp_eq_u32_e64 s[2:3], 4, v180
	s_nop 1
	v_cndmask_b32_e64 v147, v147, v146, s[2:3]
; DI float bflo(unsigned v) { return __uint_as_float(v << 16); }
; DI float bfhi(unsigned v) { return __uint_as_float(v & 0xffff0000u); }
; template <int EPI>
; DI void gemm_tile(const Params& p, int layer, int mt, int nt, u16* sm, int wv) {
;     ...
;       for (int t = 0; t < 16; ++t) {
;         const int row = (lane >> 4) + 4 * t;
;         const f32x4 a4 = *(const f32x4*)(stg + row * 68 + kc * 4);
;         const float v0 = bflo(xb[t][0]) + a4[0], v1 = bfhi(xb[t][0]) + a4[1], v2 = bflo(xb[t][1]) + a4[2], v3 = bfhi(xb[t][1]) + a4[3];
;         float sq = v0 * v0 + v1 * v1 + v2 * v2 + v3 * v3;
;         u32x2 pv = {pk2(v0, v1), pk2(v2, v3)};
;         if (has_next) *(u32x2*)(xrow + (size_t)row * DM) = pv;
;         else *(u32x2*)(x2row + (size_t)row * DM) = pv;
;         sq += shx(sq, lane, 1); sq += shx(sq, lane, 2); sq += shx(sq, lane, 4); sq += shx(sq, lane, 8);
;         if (kc == 0) atomicAdd(ssn + mrow0 + row, sq);
;       }
.LBB0_449:
	s_waitcnt lgkmcnt(0)
	ds_read_b128 v[28:31], v69 offset:5440
	v_lshlrev_b32_e32 v32, 16, v26
	v_and_b32_e32 v33, 0xffff0000, v26
	v_lshlrev_b32_e32 v26, 16, v27
	v_and_b32_e32 v27, 0xffff0000, v27
	s_waitcnt lgkmcnt(0)
	v_pk_add_f32 v[28:29], v[28:29], v[32:33]
	v_pk_add_f32 v[26:27], v[30:31], v[26:27]
	v_pk_mul_f32 v[30:31], v[28:29], v[28:29]
	v_pk_mul_f32 v[32:33], v[26:27], v[26:27]
	v_add_f32_e32 v30, v30, v31
	v_lshlrev_b32_e32 v0, 10, v124
	v_add_f32_e32 v30, v32, v30
	v_add_f32_e32 v30, v33, v30
	v_lshlrev_b32_e32 v0, 1, v0
	v_cvt_pk_bf16_f32 v28, v28, v29
	v_cvt_pk_bf16_f32 v29, v26, v27
	v_lshl_add_u64 v[26:27], v[10:11], 0, v[0:1]
	s_nop 1
	v_mov_b32_dpp v0, v30 quad_perm:[1,0,3,2] row_mask:0xf bank_mask:0xf
	global_store_dwordx2 v[26:27], v[28:29], off
	s_waitcnt lgkmcnt(0)
	v_add_f32_e32 v0, v30, v0
	s_nop 1
	v_mov_b32_dpp v26, v0 quad_perm:[2,3,0,1] row_mask:0xf bank_mask:0xf
	s_waitcnt lgkmcnt(0)
	v_add_f32_e32 v0, v0, v26
	s_nop 1
	v_mov_b32_dpp v26, v0 row_half_mirror row_mask:0xf bank_mask:0xf
	s_waitcnt lgkmcnt(0)
	v_add_f32_e32 v0, v0, v26
	s_nop 1
	v_mov_b32_dpp v26, v0 row_mirror row_mask:0xf bank_mask:0xf
	v_add_f32_e32 v146, v0, v26
	v_cmp_eq_u32_e64 s[2:3], 5, v180
	s_nop 1
	v_cndmask_b32_e64 v147, v147, v146, s[2:3]
.LBB0_451:
	s_waitcnt lgkmcnt(0)
	ds_read_b128 v[26:29], v69 offset:6528
	v_lshlrev_b32_e32 v30, 16, v24
	v_and_b32_e32 v31, 0xffff0000, v24
	v_lshlrev_b32_e32 v24, 16, v25
	v_and_b32_e32 v25, 0xffff0000, v25
	s_waitcnt lgkmcnt(0)
	v_pk_add_f32 v[26:27], v[26:27], v[30:31]
	v_pk_add_f32 v[24:25], v[28:29], v[24:25]
	v_pk_mul_f32 v[28:29], v[26:27], v[26:27]
	v_pk_mul_f32 v[30:31], v[24:25], v[24:25]
	v_add_f32_e32 v28, v28, v29
	v_lshlrev_b32_e32 v0, 10, v122
	v_add_f32_e32 v28, v30, v28
	v_add_f32_e32 v28, v31, v28
	v_lshlrev_b32_e32 v0, 1, v0
	v_cvt_pk_bf16_f32 v26, v26, v27
	v_cvt_pk_bf16_f32 v27, v24, v25
	v_lshl_add_u64 v[24:25], v[10:11], 0, v[0:1]
	s_nop 1
	v_mov_b32_dpp v0, v28 quad_perm:[1,0,3,2] row_mask:0xf bank_mask:0xf
	global_store_dwordx2 v[24:25], v[26:27], off
	s_waitcnt lgkmcnt(0)
	v_add_f32_e32 v0, v28, v0
	s_nop 1
	v_mov_b32_dpp v24, v0 quad_perm:[2,3,0,1] row_mask:0xf bank_mask:0xf
	s_waitcnt lgkmcnt(0)
	v_add_f32_e32 v0, v0, v24
	s_nop 1
	v_mov_b32_dpp v24, v0 row_half_mirror row_mask:0xf bank_mask:0xf
	s_waitcnt lgkmcnt(0)
	v_add_f32_e32 v0, v0, v24
	s_nop 1
	v_mov_b32_dpp v24, v0 row_mirror row_mask:0xf bank_mask:0xf
	v_add_f32_e32 v146, v0, v24
	v_cmp_eq_u32_e64 s[2:3], 6, v180
	s_nop 1
	v_cndmask_b32_e64 v147, v147, v146, s[2:3]
.LBB0_453:
	s_waitcnt lgkmcnt(0)
	ds_read_b128 v[24:27], v69 offset:7616
	v_lshlrev_b32_e32 v28, 16, v22
	v_and_b32_e32 v29, 0xffff0000, v22
	v_lshlrev_b32_e32 v22, 16, v23
	v_and_b32_e32 v23, 0xffff0000, v23
	s_waitcnt lgkmcnt(0)
	v_pk_add_f32 v[24:25], v[24:25], v[28:29]
	v_pk_add_f32 v[22:23], v[26:27], v[22:23]
	v_pk_mul_f32 v[26:27], v[24:25], v[24:25]
	v_pk_mul_f32 v[28:29], v[22:23], v[22:23]
	v_add_f32_e32 v26, v26, v27
	v_lshlrev_b32_e32 v0, 10, v120
	v_add_f32_e32 v26, v28, v26
	v_add_f32_e32 v26, v29, v26
	v_lshlrev_b32_e32 v0, 1, v0
	v_cvt_pk_bf16_f32 v24, v24, v25
	v_cvt_pk_bf16_f32 v25, v22, v23
	v_lshl_add_u64 v[22:23], v[10:11], 0, v[0:1]
	s_nop 1
	v_mov_b32_dpp v0, v26 quad_perm:[1,0,3,2] row_mask:0xf bank_mask:0xf
	global_store_dwordx2 v[22:23], v[24:25], off
	s_waitcnt lgkmcnt(0)
	v_add_f32_e32 v0, v26, v0
	s_nop 1
	v_mov_b32_dpp v22, v0 quad_perm:[2,3,0,1] row_mask:0xf bank_mask:0xf
	s_waitcnt lgkmcnt(0)
	v_add_f32_e32 v0, v0, v22
	s_nop 1
	v_mov_b32_dpp v22, v0 row_half_mirror row_mask:0xf bank_mask:0xf
	s_waitcnt lgkmcnt(0)
	v_add_f32_e32 v0, v0, v22
	s_nop 1
	v_mov_b32_dpp v22, v0 row_mirror row_mask:0xf bank_mask:0xf
	v_add_f32_e32 v146, v0, v22
	v_cmp_eq_u32_e64 s[2:3], 7, v180
	s_nop 1
	v_cndmask_b32_e64 v147, v147, v146, s[2:3]
.LBB0_455:
	s_waitcnt lgkmcnt(0)
	ds_read_b128 v[22:25], v69 offset:8704
	v_lshlrev_b32_e32 v26, 16, v20
	v_and_b32_e32 v27, 0xffff0000, v20
	v_lshlrev_b32_e32 v20, 16, v21
	v_and_b32_e32 v21, 0xffff0000, v21
	s_waitcnt lgkmcnt(0)
	v_pk_add_f32 v[22:23], v[22:23], v[26:27]
	v_pk_add_f32 v[20:21], v[24:25], v[20:21]
	v_pk_mul_f32 v[24:25], v[22:23], v[22:23]
	v_pk_mul_f32 v[26:27], v[20:21], v[20:21]
	v_add_f32_e32 v24, v24, v25
	v_lshlrev_b32_e32 v0, 10, v118
	v_add_f32_e32 v24, v26, v24
	v_add_f32_e32 v24, v27, v24
	v_lshlrev_b32_e32 v0, 1, v0
	v_cvt_pk_bf16_f32 v22, v22, v23
	v_cvt_pk_bf16_f32 v23, v20, v21
	v_lshl_add_u64 v[20:21], v[10:11], 0, v[0:1]
	s_nop 1
	v_mov_b32_dpp v0, v24 quad_perm:[1,0,3,2] row_mask:0xf bank_mask:0xf
	global_store_dwordx2 v[20:21], v[22:23], off
	s_waitcnt lgkmcnt(0)
	v_add_f32_e32 v0, v24, v0
	s_nop 1
	v_mov_b32_dpp v20, v0 quad_perm:[2,3,0,1] row_mask:0xf bank_mask:0xf
	s_waitcnt lgkmcnt(0)
	v_add_f32_e32 v0, v0, v20
	s_nop 1
	v_mov_b32_dpp v20, v0 row_half_mirror row_mask:0xf bank_mask:0xf
	s_waitcnt lgkmcnt(0)
	v_add_f32_e32 v0, v0, v20
	s_nop 1
	v_mov_b32_dpp v20, v0 row_mirror row_mask:0xf bank_mask:0xf
	v_add_f32_e32 v146, v0, v20
	v_cmp_eq_u32_e64 s[2:3], 8, v180
	s_nop 1
	v_cndmask_b32_e64 v147, v147, v146, s[2:3]
; DI float bflo(unsigned v) { return __uint_as_float(v << 16); }
; DI float bfhi(unsigned v) { return __uint_as_float(v & 0xffff0000u); }
; template <int EPI>
; DI void gemm_tile(const Params& p, int layer, int mt, int nt, u16* sm, int wv) {
;     ...
;       for (int t = 0; t < 16; ++t) {
;         const int row = (lane >> 4) + 4 * t;
;         const f32x4 a4 = *(const f32x4*)(stg + row * 68 + kc * 4);
;         const float v0 = bflo(xb[t][0]) + a4[0], v1 = bfhi(xb[t][0]) + a4[1], v2 = bflo(xb[t][1]) + a4[2], v3 = bfhi(xb[t][1]) + a4[3];
;         float sq = v0 * v0 + v1 * v1 + v2 * v2 + v3 * v3;
;         u32x2 pv = {pk2(v0, v1), pk2(v2, v3)};
;         if (has_next) *(u32x2*)(xrow + (size_t)row * DM) = pv;
;         else *(u32x2*)(x2row + (size_t)row * DM) = pv;
;         sq += shx(sq, lane, 1); sq += shx(sq, lane, 2); sq += shx(sq, lane, 4); sq += shx(sq, lane, 8);
;         if (kc == 0) atomicAdd(ssn + mrow0 + row, sq);
;       }
.LBB0_457:
	s_waitcnt lgkmcnt(0)
	ds_read_b128 v[20:23], v69 offset:9792
	v_lshlrev_b32_e32 v24, 16, v18
	v_and_b32_e32 v25, 0xffff0000, v18
	v_lshlrev_b32_e32 v18, 16, v19
	v_and_b32_e32 v19, 0xffff0000, v19
	s_waitcnt lgkmcnt(0)
	v_pk_add_f32 v[20:21], v[20:21], v[24:25]
	v_pk_add_f32 v[18:19], v[22:23], v[18:19]
	v_pk_mul_f32 v[22:23], v[20:21], v[20:21]
	v_pk_mul_f32 v[24:25], v[18:19], v[18:19]
	v_add_f32_e32 v22, v22, v23
	v_lshlrev_b32_e32 v0, 10, v116
	v_add_f32_e32 v22, v24, v22
	v_add_f32_e32 v22, v25, v22
	v_lshlrev_b32_e32 v0, 1, v0
	v_cvt_pk_bf16_f32 v20, v20, v21
	v_cvt_pk_bf16_f32 v21, v18, v19
	v_lshl_add_u64 v[18:19], v[10:11], 0, v[0:1]
	s_nop 1
	v_mov_b32_dpp v0, v22 quad_perm:[1,0,3,2] row_mask:0xf bank_mask:0xf
	global_store_dwordx2 v[18:19], v[20:21], off
	s_waitcnt lgkmcnt(0)
	v_add_f32_e32 v0, v22, v0
	s_nop 1
	v_mov_b32_dpp v18, v0 quad_perm:[2,3,0,1] row_mask:0xf bank_mask:0xf
	s_waitcnt lgkmcnt(0)
	v_add_f32_e32 v0, v0, v18
	s_nop 1
	v_mov_b32_dpp v18, v0 row_half_mirror row_mask:0xf bank_mask:0xf
	s_waitcnt lgkmcnt(0)
	v_add_f32_e32 v0, v0, v18
	s_nop 1
	v_mov_b32_dpp v18, v0 row_mirror row_mask:0xf bank_mask:0xf
	v_add_f32_e32 v146, v0, v18
	v_cmp_eq_u32_e64 s[2:3], 9, v180
	s_nop 1
	v_cndmask_b32_e64 v147, v147, v146, s[2:3]
.LBB0_459:
	s_waitcnt lgkmcnt(0)
	ds_read_b128 v[18:21], v69 offset:10880
	v_lshlrev_b32_e32 v22, 16, v16
	v_and_b32_e32 v23, 0xffff0000, v16
	v_lshlrev_b32_e32 v16, 16, v17
	v_and_b32_e32 v17, 0xffff0000, v17
	s_waitcnt lgkmcnt(0)
	v_pk_add_f32 v[18:19], v[18:19], v[22:23]
	v_pk_add_f32 v[16:17], v[20:21], v[16:17]
	v_pk_mul_f32 v[20:21], v[18:19], v[18:19]
	v_pk_mul_f32 v[22:23], v[16:17], v[16:17]
	v_add_f32_e32 v20, v20, v21
	v_lshlrev_b32_e32 v0, 10, v114
	v_add_f32_e32 v20, v22, v20
	v_add_f32_e32 v20, v23, v20
	v_lshlrev_b32_e32 v0, 1, v0
	v_cvt_pk_bf16_f32 v18, v18, v19
	v_cvt_pk_bf16_f32 v19, v16, v17
	v_lshl_add_u64 v[16:17], v[10:11], 0, v[0:1]
	s_nop 1
	v_mov_b32_dpp v0, v20 quad_perm:[1,0,3,2] row_mask:0xf bank_mask:0xf
	global_store_dwordx2 v[16:17], v[18:19], off
	s_waitcnt lgkmcnt(0)
	v_add_f32_e32 v0, v20, v0
	s_nop 1
	v_mov_b32_dpp v16, v0 quad_perm:[2,3,0,1] row_mask:0xf bank_mask:0xf
	s_waitcnt lgkmcnt(0)
	v_add_f32_e32 v0, v0, v16
	s_nop 1
	v_mov_b32_dpp v16, v0 row_half_mirror row_mask:0xf bank_mask:0xf
	s_waitcnt lgkmcnt(0)
	v_add_f32_e32 v0, v0, v16
	s_nop 1
	v_mov_b32_dpp v16, v0 row_mirror row_mask:0xf bank_mask:0xf
	v_add_f32_e32 v146, v0, v16
	v_cmp_eq_u32_e64 s[2:3], 10, v180
	s_nop 1
	v_cndmask_b32_e64 v147, v147, v146, s[2:3]
.LBB0_461:
	s_waitcnt lgkmcnt(0)
	ds_read_b128 v[16:19], v69 offset:11968
	v_lshlrev_b32_e32 v20, 16, v14
	v_and_b32_e32 v21, 0xffff0000, v14
	v_lshlrev_b32_e32 v14, 16, v15
	v_and_b32_e32 v15, 0xffff0000, v15
	s_waitcnt lgkmcnt(0)
	v_pk_add_f32 v[16:17], v[16:17], v[20:21]
	v_pk_add_f32 v[14:15], v[18:19], v[14:15]
	v_pk_mul_f32 v[18:19], v[16:17], v[16:17]
	v_pk_mul_f32 v[20:21], v[14:15], v[14:15]
	v_add_f32_e32 v18, v18, v19
	v_lshlrev_b32_e32 v0, 10, v112
	v_add_f32_e32 v18, v20, v18
	v_add_f32_e32 v18, v21, v18
	v_lshlrev_b32_e32 v0, 1, v0
	v_cvt_pk_bf16_f32 v16, v16, v17
	v_cvt_pk_bf16_f32 v17, v14, v15
	v_lshl_add_u64 v[14:15], v[10:11], 0, v[0:1]
	s_nop 1
	v_mov_b32_dpp v0, v18 quad_perm:[1,0,3,2] row_mask:0xf bank_mask:0xf
	global_store_dwordx2 v[14:15], v[16:17], off
	s_waitcnt lgkmcnt(0)
	v_add_f32_e32 v0, v18, v0
	s_nop 1
	v_mov_b32_dpp v14, v0 quad_perm:[2,3,0,1] row_mask:0xf bank_mask:0xf
	s_waitcnt lgkmcnt(0)
	v_add_f32_e32 v0, v0, v14
	s_nop 1
	v_mov_b32_dpp v14, v0 row_half_mirror row_mask:0xf bank_mask:0xf
	s_waitcnt lgkmcnt(0)
	v_add_f32_e32 v0, v0, v14
	s_nop 1
	v_mov_b32_dpp v14, v0 row_mirror row_mask:0xf bank_mask:0xf
	v_add_f32_e32 v146, v0, v14
	v_cmp_eq_u32_e64 s[2:3], 11, v180
	s_nop 1
	v_cndmask_b32_e64 v147, v147, v146, s[2:3]
.LBB0_463:
	s_waitcnt lgkmcnt(0)
	ds_read_b128 v[14:17], v69 offset:13056
	s_waitcnt vmcnt(14)
	v_lshlrev_b32_e32 v18, 16, v12
	v_and_b32_e32 v19, 0xffff0000, v12
	v_lshlrev_b32_e32 v12, 16, v13
	v_and_b32_e32 v13, 0xffff0000, v13
	s_waitcnt lgkmcnt(0)
	v_pk_add_f32 v[14:15], v[14:15], v[18:19]
	v_pk_add_f32 v[12:13], v[16:17], v[12:13]
	v_pk_mul_f32 v[16:17], v[14:15], v[14:15]
	v_pk_mul_f32 v[18:19], v[12:13], v[12:13]
	v_add_f32_e32 v16, v16, v17
	v_lshlrev_b32_e32 v0, 10, v108
	v_add_f32_e32 v16, v18, v16
	v_add_f32_e32 v16, v19, v16
	v_lshlrev_b32_e32 v0, 1, v0
	v_cvt_pk_bf16_f32 v14, v14, v15
	v_cvt_pk_bf16_f32 v15, v12, v13
	v_lshl_add_u64 v[12:13], v[10:11], 0, v[0:1]
	s_nop 1
	v_mov_b32_dpp v0, v16 quad_perm:[1,0,3,2] row_mask:0xf bank_mask:0xf
	global_store_dwordx2 v[12:13], v[14:15], off
	s_waitcnt lgkmcnt(0)
	v_add_f32_e32 v0, v16, v0
	s_nop 1
	v_mov_b32_dpp v12, v0 quad_perm:[2,3,0,1] row_mask:0xf bank_mask:0xf
	s_waitcnt lgkmcnt(0)
	v_add_f32_e32 v0, v0, v12
	s_nop 1
	v_mov_b32_dpp v12, v0 row_half_mirror row_mask:0xf bank_mask:0xf
	s_waitcnt lgkmcnt(0)
	v_add_f32_e32 v0, v0, v12
	s_nop 1
	v_mov_b32_dpp v12, v0 row_mirror row_mask:0xf bank_mask:0xf
	v_add_f32_e32 v146, v0, v12
	v_cmp_eq_u32_e64 s[2:3], 12, v180
	s_nop 1
	v_cndmask_b32_e64 v147, v147, v146, s[2:3]
; DI float bflo(unsigned v) { return __uint_as_float(v << 16); }
; DI float bfhi(unsigned v) { return __uint_as_float(v & 0xffff0000u); }
; template <int EPI>
; DI void gemm_tile(const Params& p, int layer, int mt, int nt, u16* sm, int wv) {
;     ...
;       for (int t = 0; t < 16; ++t) {
;         const int row = (lane >> 4) + 4 * t;
;         const f32x4 a4 = *(const f32x4*)(stg + row * 68 + kc * 4);
;         const float v0 = bflo(xb[t][0]) + a4[0], v1 = bfhi(xb[t][0]) + a4[1], v2 = bflo(xb[t][1]) + a4[2], v3 = bfhi(xb[t][1]) + a4[3];
;         float sq = v0 * v0 + v1 * v1 + v2 * v2 + v3 * v3;
;         u32x2 pv = {pk2(v0, v1), pk2(v2, v3)};
;         if (has_next) *(u32x2*)(xrow + (size_t)row * DM) = pv;
;         else *(u32x2*)(x2row + (size_t)row * DM) = pv;
;         sq += shx(sq, lane, 1); sq += shx(sq, lane, 2); sq += shx(sq, lane, 4); sq += shx(sq, lane, 8);
;         if (kc == 0) atomicAdd(ssn + mrow0 + row, sq);
;       }
.LBB0_465:
	s_waitcnt lgkmcnt(0)
	ds_read_b128 v[12:15], v69 offset:14144
	s_waitcnt vmcnt(14)
	v_lshlrev_b32_e32 v16, 16, v8
	v_and_b32_e32 v17, 0xffff0000, v8
	v_lshlrev_b32_e32 v8, 16, v9
	v_and_b32_e32 v9, 0xffff0000, v9
	s_waitcnt lgkmcnt(0)
	v_pk_add_f32 v[12:13], v[12:13], v[16:17]
	v_pk_add_f32 v[8:9], v[14:15], v[8:9]
	v_pk_mul_f32 v[14:15], v[12:13], v[12:13]
	v_pk_mul_f32 v[16:17], v[8:9], v[8:9]
	v_add_f32_e32 v14, v14, v15
	v_lshlrev_b32_e32 v0, 10, v106
	v_add_f32_e32 v14, v16, v14
	v_add_f32_e32 v14, v17, v14
	v_lshlrev_b32_e32 v0, 1, v0
	v_cvt_pk_bf16_f32 v12, v12, v13
	v_cvt_pk_bf16_f32 v13, v8, v9
	v_lshl_add_u64 v[8:9], v[10:11], 0, v[0:1]
	s_nop 1
	v_mov_b32_dpp v0, v14 quad_perm:[1,0,3,2] row_mask:0xf bank_mask:0xf
	global_store_dwordx2 v[8:9], v[12:13], off
	s_waitcnt lgkmcnt(0)
	v_add_f32_e32 v0, v14, v0
	s_nop 1
	v_mov_b32_dpp v8, v0 quad_perm:[2,3,0,1] row_mask:0xf bank_mask:0xf
	s_waitcnt lgkmcnt(0)
	v_add_f32_e32 v0, v0, v8
	s_nop 1
	v_mov_b32_dpp v8, v0 row_half_mirror row_mask:0xf bank_mask:0xf
	s_waitcnt lgkmcnt(0)
	v_add_f32_e32 v0, v0, v8
	s_nop 1
	v_mov_b32_dpp v8, v0 row_mirror row_mask:0xf bank_mask:0xf
	v_add_f32_e32 v146, v0, v8
	v_cmp_eq_u32_e64 s[2:3], 13, v180
	s_nop 1
	v_cndmask_b32_e64 v147, v147, v146, s[2:3]
.LBB0_467:
	ds_read_b128 v[12:15], v69 offset:15232
	s_waitcnt vmcnt(14) lgkmcnt(1)
	v_lshlrev_b32_e32 v8, 16, v6
	v_and_b32_e32 v9, 0xffff0000, v6
	v_lshlrev_b32_e32 v6, 16, v7
	v_and_b32_e32 v7, 0xffff0000, v7
	s_waitcnt lgkmcnt(0)
	v_pk_add_f32 v[8:9], v[12:13], v[8:9]
	v_pk_add_f32 v[6:7], v[14:15], v[6:7]
	v_pk_mul_f32 v[12:13], v[8:9], v[8:9]
	v_pk_mul_f32 v[14:15], v[6:7], v[6:7]
	v_add_f32_e32 v12, v12, v13
	v_lshlrev_b32_e32 v0, 10, v103
	v_add_f32_e32 v12, v14, v12
	v_add_f32_e32 v12, v15, v12
	v_lshlrev_b32_e32 v0, 1, v0
	v_cvt_pk_bf16_f32 v8, v8, v9
	v_cvt_pk_bf16_f32 v9, v6, v7
	v_lshl_add_u64 v[6:7], v[10:11], 0, v[0:1]
	s_nop 1
	v_mov_b32_dpp v0, v12 quad_perm:[1,0,3,2] row_mask:0xf bank_mask:0xf
	global_store_dwordx2 v[6:7], v[8:9], off
	s_waitcnt lgkmcnt(0)
	v_add_f32_e32 v0, v12, v0
	s_nop 1
	v_mov_b32_dpp v6, v0 quad_perm:[2,3,0,1] row_mask:0xf bank_mask:0xf
	s_waitcnt lgkmcnt(0)
	v_add_f32_e32 v0, v0, v6
	s_nop 1
	v_mov_b32_dpp v6, v0 row_half_mirror row_mask:0xf bank_mask:0xf
	s_waitcnt lgkmcnt(0)
	v_add_f32_e32 v0, v0, v6
	s_nop 1
	v_mov_b32_dpp v6, v0 row_mirror row_mask:0xf bank_mask:0xf
	v_add_f32_e32 v146, v0, v6
	v_cmp_eq_u32_e64 s[2:3], 14, v180
	s_nop 1
	v_cndmask_b32_e64 v147, v147, v146, s[2:3]
.LBB0_469:
	s_waitcnt lgkmcnt(0)
	ds_read_b128 v[6:9], v69 offset:16320
	s_waitcnt vmcnt(14)
	v_lshlrev_b32_e32 v12, 16, v2
	v_and_b32_e32 v13, 0xffff0000, v2
	v_lshlrev_b32_e32 v2, 16, v3
	v_and_b32_e32 v3, 0xffff0000, v3
	s_waitcnt lgkmcnt(0)
	v_pk_add_f32 v[6:7], v[6:7], v[12:13]
	v_pk_add_f32 v[2:3], v[8:9], v[2:3]
	v_pk_mul_f32 v[8:9], v[6:7], v[6:7]
	v_pk_mul_f32 v[12:13], v[2:3], v[2:3]
	v_add_f32_e32 v8, v8, v9
	v_lshlrev_b32_e32 v0, 10, v102
	v_add_f32_e32 v8, v12, v8
	v_add_f32_e32 v8, v13, v8
	v_lshlrev_b32_e32 v0, 1, v0
	v_cvt_pk_bf16_f32 v6, v6, v7
	v_cvt_pk_bf16_f32 v7, v2, v3
	v_lshl_add_u64 v[2:3], v[10:11], 0, v[0:1]
	s_nop 1
	v_mov_b32_dpp v0, v8 quad_perm:[1,0,3,2] row_mask:0xf bank_mask:0xf
	global_store_dwordx2 v[2:3], v[6:7], off
	s_waitcnt lgkmcnt(0)
	v_add_f32_e32 v0, v8, v0
	s_nop 1
	v_mov_b32_dpp v2, v0 quad_perm:[2,3,0,1] row_mask:0xf bank_mask:0xf
	s_waitcnt lgkmcnt(0)
	v_add_f32_e32 v0, v0, v2
	s_nop 1
	v_mov_b32_dpp v2, v0 row_half_mirror row_mask:0xf bank_mask:0xf
	s_waitcnt lgkmcnt(0)
	v_add_f32_e32 v0, v0, v2
	s_nop 1
	v_mov_b32_dpp v2, v0 row_mirror row_mask:0xf bank_mask:0xf
	v_add_f32_e32 v146, v0, v2
	v_cmp_eq_u32_e64 s[2:3], 15, v180
	s_nop 1
	v_cndmask_b32_e64 v147, v147, v146, s[2:3]
	v_lshl_add_u32 v148, v180, 4, v66
	v_mov_b32_e32 v149, v1
	v_lshl_add_u64 v[148:149], v[4:5], 0, v[148:149]
	global_atomic_add_f32 v[148:149], v147, off
	s_branch .LBB0_394
